# prologue mem loop: 8 row loads issued together (on early-invalidate version)
# baseline (speedup 1.0000x reference)
; __device__ __forceinline__ unsigned cvt_pk_bf16(float lo, float hi) { const f32x2_t v = {lo, hi}; const bf16x2_t r = __builtin_convertvector(v, bf16x2_t); return __builtin_bit_cast(unsigned, r); }
; __device__ __forceinline__ void p_prologue(Frame& F, int stage, int part, int nparts) {
;     ...
;         for (int m = gw; m < MEMROWS; m += NGW) {
;             const f32x4* xr = (const f32x4*)(mem + (size_t)m * DM) + lane; u32x2* br = (u32x2*)(MB + (size_t)m * DM) + lane; float s = 0.f;
; #pragma unroll
;             for (int j = 0; j < 8; ++j) { const f32x4 v = xr[64 * j]; u32x2 w; w.x = cvt_pk_bf16(v[0], v[1]); w.y = cvt_pk_bf16(v[2], v[3]); br[64 * j] = w; s += (v[0] * v[0] + v[1] * v[1]) + (v[2] * v[2] + v[3] * v[3]); }
;             s = wave_sum(s); if (lane == 0) RSM[m] = __builtin_amdgcn_rsqf(s * (1.0f / DM) + EPS);
;         }
.LBB0_34:
	s_waitcnt lgkmcnt(0)
	global_load_dwordx4 v[16:19], v[4:5], off offset:-4096
	global_load_dwordx4 v[20:23], v[4:5], off offset:-3072
	global_load_dwordx4 v[24:27], v[4:5], off offset:-2048
	global_load_dwordx4 v[28:31], v[4:5], off offset:-1024
	global_load_dwordx4 v[32:35], v[4:5], off
	global_load_dwordx4 v[36:39], v[4:5], off offset:1024
	global_load_dwordx4 v[40:43], v[4:5], off offset:2048
	global_load_dwordx4 v[44:47], v[4:5], off offset:3072
	v_lshl_add_u64 v[50:51], s[54:55], 0, v[6:7]
	v_add_co_u32_e32 v48, vcc, s5, v50
	s_nop 1
	v_addc_co_u32_e32 v49, vcc, 0, v51, vcc
	s_waitcnt vmcnt(7)
	v_cvt_pk_bf16_f32 v50, v16, v17
	v_cvt_pk_bf16_f32 v51, v18, v19
	global_store_dwordx2 v[48:49], v[50:51], off
	v_mul_f32_e32 v17, v17, v17
	v_mul_f32_e32 v19, v19, v19
	v_fmac_f32_e32 v17, v16, v16
	v_fmac_f32_e32 v19, v18, v18
	v_add_f32_e32 v16, v17, v19
	s_waitcnt vmcnt(7)
	v_cvt_pk_bf16_f32 v52, v20, v21
	v_cvt_pk_bf16_f32 v53, v22, v23
	global_store_dwordx2 v[48:49], v[52:53], off offset:512
	v_mul_f32_e32 v17, v21, v21
	v_mul_f32_e32 v18, v23, v23
	v_fmac_f32_e32 v17, v20, v20
	v_fmac_f32_e32 v18, v22, v22
	v_add_f32_e32 v17, v17, v18
	v_add_f32_e32 v16, v16, v17
	s_waitcnt vmcnt(7)
	v_cvt_pk_bf16_f32 v54, v24, v25
	v_cvt_pk_bf16_f32 v55, v26, v27
	global_store_dwordx2 v[48:49], v[54:55], off offset:1024
	v_mul_f32_e32 v17, v25, v25
	v_mul_f32_e32 v18, v27, v27
	v_fmac_f32_e32 v17, v24, v24
	v_fmac_f32_e32 v18, v26, v26
	v_add_f32_e32 v17, v17, v18
	v_add_f32_e32 v16, v16, v17
	s_waitcnt vmcnt(7)
	v_cvt_pk_bf16_f32 v56, v28, v29
	v_cvt_pk_bf16_f32 v57, v30, v31
	global_store_dwordx2 v[48:49], v[56:57], off offset:1536
	v_mul_f32_e32 v17, v29, v29
	v_mul_f32_e32 v18, v31, v31
	v_fmac_f32_e32 v17, v28, v28
	v_fmac_f32_e32 v18, v30, v30
	v_add_f32_e32 v17, v17, v18
	v_add_f32_e32 v16, v16, v17
	s_waitcnt vmcnt(7)
	v_cvt_pk_bf16_f32 v58, v32, v33
	v_cvt_pk_bf16_f32 v59, v34, v35
	global_store_dwordx2 v[48:49], v[58:59], off offset:2048
	v_mul_f32_e32 v17, v33, v33
	v_mul_f32_e32 v18, v35, v35
	v_fmac_f32_e32 v17, v32, v32
	v_fmac_f32_e32 v18, v34, v34
	v_add_f32_e32 v17, v17, v18
	v_add_f32_e32 v16, v16, v17
	s_waitcnt vmcnt(7)
	v_cvt_pk_bf16_f32 v60, v36, v37
	v_cvt_pk_bf16_f32 v61, v38, v39
	global_store_dwordx2 v[48:49], v[60:61], off offset:2560
	v_mul_f32_e32 v17, v37, v37
	v_mul_f32_e32 v18, v39, v39
	v_fmac_f32_e32 v17, v36, v36
	v_fmac_f32_e32 v18, v38, v38
	v_add_f32_e32 v17, v17, v18
	v_add_f32_e32 v16, v16, v17
	s_waitcnt vmcnt(7)
	v_cvt_pk_bf16_f32 v62, v40, v41
	v_cvt_pk_bf16_f32 v63, v42, v43
	global_store_dwordx2 v[48:49], v[62:63], off offset:3072
	v_mul_f32_e32 v17, v41, v41
	v_mul_f32_e32 v18, v43, v43
	v_fmac_f32_e32 v17, v40, v40
	v_fmac_f32_e32 v18, v42, v42
	v_add_f32_e32 v17, v17, v18
	v_add_f32_e32 v16, v16, v17
	s_waitcnt vmcnt(7)
	v_cvt_pk_bf16_f32 v64, v44, v45
	v_cvt_pk_bf16_f32 v65, v46, v47
	global_store_dwordx2 v[48:49], v[64:65], off offset:3584
	v_mul_f32_e32 v17, v45, v45
	v_mul_f32_e32 v18, v47, v47
	v_fmac_f32_e32 v17, v44, v44
	v_fmac_f32_e32 v18, v46, v46
	v_add_f32_e32 v17, v17, v18
	v_add_f32_e32 v16, v16, v17
	ds_bpermute_b32 v17, v8, v16
	s_waitcnt lgkmcnt(0)
	v_add_f32_e32 v16, v16, v17
	ds_bpermute_b32 v17, v9, v16
	s_waitcnt lgkmcnt(0)
	v_add_f32_e32 v16, v16, v17
	ds_bpermute_b32 v17, v11, v16
	s_waitcnt lgkmcnt(0)
	v_add_f32_e32 v16, v16, v17
	ds_bpermute_b32 v17, v12, v16
	s_waitcnt lgkmcnt(0)
	v_add_f32_e32 v16, v16, v17
	ds_bpermute_b32 v17, v13, v16
	s_waitcnt lgkmcnt(0)
	v_add_f32_e32 v16, v16, v17
	ds_bpermute_b32 v17, v14, v16
	s_and_saveexec_b64 s[24:25], s[0:1]
	s_cbranch_execz .LBB0_33
	s_waitcnt lgkmcnt(0)
	v_add_f32_e32 v16, v16, v17
	v_fmamk_f32 v16, v16, 0x3a000000, v15
	v_rsq_f32_e32 v16, v16
	s_add_u32 s28, s54, s13
	s_addc_u32 s29, s55, s26
	global_store_dword v3, v16, s[28:29]
	s_branch .LBB0_33
